# cross-segment overlap: the next chunk's alpha/beta (softplus decay, sigmoid gate) computed by wave 3 while it would idle in the chunk's second stage; the serial section at the chunk start runs for the
# baseline (speedup 1.0000x reference)
; __device__ __forceinline__ float sigm(float x) { return __builtin_amdgcn_rcpf(1.f + __expf(-x)); }
; __device__ __forceinline__ void dn_task(const Params& p, int l, int task, char* smem) {
;     ...
;     if (tid >= 224) {
;       const int t = tid - 224;
;       const float xx = ra + dtb;
;       const float sp = xx > 20.f ? xx : log1pf(__expf(xx));
;       al[t] = __expf(-Aexp * sp);
;       al[32 + t] = sigm(rb);
;     }
.LBB0_195:
	s_or_b64 exec, exec, s[70:71]
	s_and_saveexec_b64 s[60:61], s[50:51]
	s_cbranch_execz .LBB0_199
	s_cmp_lg_u32 s81, 0
	s_cbranch_scc1 .LBB0_199

; __device__ __forceinline__ float sigm(float x) { return __builtin_amdgcn_rcpf(1.f + __expf(-x)); }
; __device__ __forceinline__ void dn_task(const Params& p, int l, int task, char* smem) {
;     ...
;     if (tid >= 224) {
;       const int t = tid - 224;
;       const float xx = ra + dtb;
;       const float sp = xx > 20.f ? xx : log1pf(__expf(xx));
;       al[t] = __expf(-Aexp * sp);
;       al[32 + t] = sigm(rb);
;     }
.Ldc_q2:
	ds_read_b128 v[26:29], v224 offset:0
	ds_read_b128 v[30:33], v224 offset:16
	ds_read_b128 v[34:37], v224 offset:32
	ds_read_b128 v[38:41], v224 offset:48
	v_lshlrev_b32_e32 v245, 2, v222
	v_add_u32_e32 v245, 0x13700, v245
	ds_read_b32 v42, v245 offset:0
	s_waitcnt lgkmcnt(0)
	v_mul_f32_e32 v26, v42, v26
	v_mul_f32_e32 v27, v42, v27
	v_mul_f32_e32 v28, v42, v28
	v_mul_f32_e32 v29, v42, v29
	v_mul_f32_e32 v30, v42, v30
	v_mul_f32_e32 v31, v42, v31
	v_mul_f32_e32 v32, v42, v32
	v_mul_f32_e32 v33, v42, v33
	v_mul_f32_e32 v34, v42, v34
	v_mul_f32_e32 v35, v42, v35
	v_mul_f32_e32 v36, v42, v36
	v_mul_f32_e32 v37, v42, v37
	v_mul_f32_e32 v38, v42, v38
	v_mul_f32_e32 v39, v42, v39
	v_mul_f32_e32 v40, v42, v40
	v_mul_f32_e32 v41, v42, v41
	s_nop 1
	v_mfma_f32_16x16x4_f32 v[58:61], v26, v10, 0
	v_mfma_f32_16x16x4_f32 v[58:61], v27, v11, v[58:61]
	v_mfma_f32_16x16x4_f32 v[58:61], v28, v12, v[58:61]
	v_mfma_f32_16x16x4_f32 v[58:61], v29, v13, v[58:61]
	v_mfma_f32_16x16x4_f32 v[58:61], v30, v14, v[58:61]
	v_mfma_f32_16x16x4_f32 v[58:61], v31, v15, v[58:61]
	v_mfma_f32_16x16x4_f32 v[58:61], v32, v16, v[58:61]
	v_mfma_f32_16x16x4_f32 v[58:61], v33, v17, v[58:61]
	v_mfma_f32_16x16x4_f32 v[58:61], v34, v18, v[58:61]
	v_mfma_f32_16x16x4_f32 v[58:61], v35, v19, v[58:61]
	v_mfma_f32_16x16x4_f32 v[58:61], v36, v20, v[58:61]
	v_mfma_f32_16x16x4_f32 v[58:61], v37, v21, v[58:61]
	v_mfma_f32_16x16x4_f32 v[58:61], v38, v22, v[58:61]
	v_mfma_f32_16x16x4_f32 v[58:61], v39, v23, v[58:61]
	v_mfma_f32_16x16x4_f32 v[58:61], v40, v24, v[58:61]
	v_mfma_f32_16x16x4_f32 v[58:61], v41, v25, v[58:61]
	ds_read_b128 v[26:29], v224 offset:4352
	ds_read_b128 v[30:33], v224 offset:4368
	ds_read_b128 v[34:37], v224 offset:4384
	ds_read_b128 v[38:41], v224 offset:4400
	v_lshlrev_b32_e32 v245, 2, v222
	v_add_u32_e32 v245, 0x13700, v245
	ds_read_b32 v42, v245 offset:64
	s_waitcnt lgkmcnt(0)
	v_mul_f32_e32 v26, v42, v26
	v_mul_f32_e32 v27, v42, v27
	v_mul_f32_e32 v28, v42, v28
	v_mul_f32_e32 v29, v42, v29
	v_mul_f32_e32 v30, v42, v30
	v_mul_f32_e32 v31, v42, v31
	v_mul_f32_e32 v32, v42, v32
	v_mul_f32_e32 v33, v42, v33
	v_mul_f32_e32 v34, v42, v34
	v_mul_f32_e32 v35, v42, v35
	v_mul_f32_e32 v36, v42, v36
	v_mul_f32_e32 v37, v42, v37
	v_mul_f32_e32 v38, v42, v38
	v_mul_f32_e32 v39, v42, v39
	v_mul_f32_e32 v40, v42, v40
	v_mul_f32_e32 v41, v42, v41
	s_nop 1
	v_mfma_f32_16x16x4_f32 v[62:65], v26, v10, 0
	v_mfma_f32_16x16x4_f32 v[62:65], v27, v11, v[62:65]
	v_mfma_f32_16x16x4_f32 v[62:65], v28, v12, v[62:65]
	v_mfma_f32_16x16x4_f32 v[62:65], v29, v13, v[62:65]
	v_mfma_f32_16x16x4_f32 v[62:65], v30, v14, v[62:65]
	v_mfma_f32_16x16x4_f32 v[62:65], v31, v15, v[62:65]
	v_mfma_f32_16x16x4_f32 v[62:65], v32, v16, v[62:65]
	v_mfma_f32_16x16x4_f32 v[62:65], v33, v17, v[62:65]
	v_mfma_f32_16x16x4_f32 v[62:65], v34, v18, v[62:65]
	v_mfma_f32_16x16x4_f32 v[62:65], v35, v19, v[62:65]
	v_mfma_f32_16x16x4_f32 v[62:65], v36, v20, v[62:65]
	v_mfma_f32_16x16x4_f32 v[62:65], v37, v21, v[62:65]
	v_mfma_f32_16x16x4_f32 v[62:65], v38, v22, v[62:65]
	v_mfma_f32_16x16x4_f32 v[62:65], v39, v23, v[62:65]
	v_mfma_f32_16x16x4_f32 v[62:65], v40, v24, v[62:65]
	v_mfma_f32_16x16x4_f32 v[62:65], v41, v25, v[62:65]
	s_cmp_eq_u32 s60, 3
	s_cbranch_scc0 .Lab_skip
	s_mov_b32 s83, s82
	s_waitcnt vmcnt(0)
	s_mov_b32 exec_lo, 0
	v_lshlrev_b32_e32 v141, 16, v242
	v_lshlrev_b32_e32 v140, 16, v243
	v_add_f32_e32 v0, v160, v141
	s_mov_b32 s70, 0x41a00000
	v_cmp_nlt_f32_e32 vcc, s70, v0
	s_and_saveexec_b64 s[70:71], vcc
	s_cbranch_execz .Lab_198
	v_mul_f32_e32 v0, 0x3fb8aa3b, v0
	v_exp_f32_e32 v0, v0
	s_mov_b32 s82, 0x3f2aaaab
	v_add_f32_e32 v12, 1.0, v0
	v_frexp_mant_f32_e32 v14, v12
	v_cvt_f64_f32_e32 v[10:11], v12
	v_frexp_exp_i32_f64_e32 v10, v[10:11]
	v_cmp_gt_f32_e32 vcc, s82, v14
	v_add_f32_e32 v13, -1.0, v12
	v_sub_f32_e32 v15, v13, v12
	v_subbrev_co_u32_e32 v18, vcc, 0, v10, vcc
	v_sub_u32_e32 v10, 0, v18
	v_sub_f32_e32 v13, v0, v13
	v_add_f32_e32 v15, 1.0, v15
	v_ldexp_f32 v11, v12, v10
	v_add_f32_e32 v13, v13, v15
	v_add_f32_e32 v12, -1.0, v11
	v_add_f32_e32 v14, 1.0, v11
	v_ldexp_f32 v10, v13, v10
	v_add_f32_e32 v13, 1.0, v12
	v_add_f32_e32 v15, -1.0, v14
	v_sub_f32_e32 v13, v11, v13
	v_sub_f32_e32 v11, v11, v15
	v_add_f32_e32 v13, v10, v13
	v_add_f32_e32 v10, v10, v11
	v_add_f32_e32 v19, v14, v10
	v_rcp_f32_e32 v21, v19
	v_sub_f32_e32 v11, v19, v14
	v_sub_f32_e32 v20, v10, v11
	v_add_f32_e32 v11, v12, v13
	v_mul_f32_e32 v23, v11, v21
	v_sub_f32_e32 v10, v11, v12
	v_mul_f32_e32 v12, v19, v23
	v_fma_f32 v14, v23, v19, -v12
	v_fmac_f32_e32 v14, v23, v20
	v_sub_f32_e32 v22, v13, v10
	v_add_f32_e32 v10, v12, v14
	v_sub_f32_e32 v13, v11, v10
	v_pk_add_f32 v[16:17], v[10:11], v[12:13] neg_lo:[0,1] neg_hi:[0,1]
	v_mov_b32_e32 v15, v10
	v_pk_add_f32 v[10:11], v[16:17], v[14:15] neg_lo:[0,1] neg_hi:[0,1]
	s_mov_b32 s82, 0x3f317218
	v_add_f32_e32 v11, v22, v11
	v_add_f32_e32 v10, v10, v11
	v_add_f32_e32 v11, v13, v10
	v_mul_f32_e32 v22, v21, v11
	v_mul_f32_e32 v12, v19, v22
	v_fma_f32 v14, v22, v19, -v12
	v_fmac_f32_e32 v14, v22, v20
	v_sub_f32_e32 v13, v13, v11
	v_add_f32_e32 v19, v10, v13
	v_add_f32_e32 v10, v12, v14
	v_sub_f32_e32 v13, v11, v10
	v_pk_add_f32 v[16:17], v[10:11], v[12:13] neg_lo:[0,1] neg_hi:[0,1]
	v_mov_b32_e32 v15, v10
	v_pk_add_f32 v[10:11], v[16:17], v[14:15] neg_lo:[0,1] neg_hi:[0,1]
	s_nop 0
	v_add_f32_e32 v11, v19, v11
	v_add_f32_e32 v10, v10, v11
	v_add_f32_e32 v11, v23, v22
	v_add_f32_e32 v10, v13, v10
	v_sub_f32_e32 v12, v11, v23
	v_mul_f32_e32 v10, v21, v10
	v_sub_f32_e32 v12, v22, v12
	v_add_f32_e32 v12, v12, v10
	v_add_f32_e32 v14, v11, v12
	v_mul_f32_e32 v15, v14, v14
; __device__ __forceinline__ float sigm(float x) { return __builtin_amdgcn_rcpf(1.f + __expf(-x)); }
; __device__ __forceinline__ void dn_task(const Params& p, int l, int task, char* smem) {
;     ...
;     if (tid >= 224) {
;       const int t = tid - 224;
;       const float xx = ra + dtb;
;       const float sp = xx > 20.f ? xx : log1pf(__expf(xx));
;       al[t] = __expf(-Aexp * sp);
;       al[32 + t] = sigm(rb);
;     }
	v_fmamk_f32 v10, v15, 0x3e9b6dac, v177
	v_fmaak_f32 v135, v15, v10, 0x3f2aaada
	v_cvt_f32_i32_e32 v10, v18
	v_sub_f32_e32 v11, v14, v11
	v_sub_f32_e32 v11, v12, v11
	v_ldexp_f32 v16, v11, 1
	v_mul_f32_e32 v11, v14, v15
	v_ldexp_f32 v13, v14, 1
	v_pk_mul_f32 v[14:15], v[10:11], v[134:135]
	s_nop 0
	v_fma_f32 v12, v10, s82, -v14
	v_fmac_f32_e32 v12, 0xb102e308, v10
	v_pk_add_f32 v[10:11], v[14:15], v[12:13]
	s_mov_b32 s82, 0x7f800000
	v_sub_f32_e32 v13, v11, v13
	v_sub_f32_e32 v13, v15, v13
	v_add_f32_e32 v17, v16, v13
	v_mov_b32_e32 v16, v14
	v_pk_add_f32 v[14:15], v[10:11], v[14:15] neg_lo:[0,1] neg_hi:[0,1]
	v_pk_add_f32 v[18:19], v[10:11], v[16:17]
	v_mov_b32_e32 v13, v10
	v_mov_b32_e32 v15, v19
	v_pk_add_f32 v[20:21], v[12:13], v[14:15] neg_lo:[0,1] neg_hi:[0,1]
	v_pk_add_f32 v[12:13], v[12:13], v[14:15]
	v_mov_b32_e32 v16, v17
	v_pk_add_f32 v[14:15], v[12:13], v[10:11] op_sel:[1,0] op_sel_hi:[0,1] neg_lo:[0,1] neg_hi:[0,1]
	v_pk_add_f32 v[22:23], v[18:19], v[14:15] op_sel_hi:[1,0] neg_lo:[0,1] neg_hi:[0,1]
	v_mov_b32_e32 v18, v19
	v_mov_b32_e32 v19, v13
	v_pk_mov_b32 v[14:15], v[10:11], v[14:15] op_sel:[1,0]
	v_mov_b32_e32 v17, v10
	v_pk_add_f32 v[14:15], v[18:19], v[14:15] neg_lo:[0,1] neg_hi:[0,1]
	v_mov_b32_e32 v22, v20
	v_pk_add_f32 v[10:11], v[16:17], v[14:15] neg_lo:[0,1] neg_hi:[0,1]
	v_mov_b32_e32 v21, v13
	v_pk_add_f32 v[14:15], v[22:23], v[10:11]
	v_cmp_neq_f32_e32 vcc, s82, v0
	v_pk_add_f32 v[16:17], v[14:15], v[14:15] op_sel:[0,1] op_sel_hi:[1,0]
	s_mov_b32 s82, 0x33800000
	v_pk_add_f32 v[12:13], v[12:13], v[16:17] op_sel:[1,0] op_sel_hi:[0,1]
	v_mov_b32_e32 v15, v12
	v_pk_add_f32 v[18:19], v[14:15], v[20:21] neg_lo:[0,1] neg_hi:[0,1]
	v_mov_b32_e32 v11, v16
	v_sub_f32_e32 v13, v14, v18
	v_pk_add_f32 v[10:11], v[10:11], v[18:19] neg_lo:[0,1] neg_hi:[0,1]
	v_sub_f32_e32 v13, v20, v13
	v_add_f32_e32 v10, v10, v13
	v_add_f32_e32 v10, v10, v11
	v_add_f32_e32 v10, v12, v10
	v_cndmask_b32_e32 v10, v181, v10, vcc
	v_cmp_ngt_f32_e32 vcc, -1.0, v0
	s_nop 1
	v_cndmask_b32_e32 v10, v184, v10, vcc
	v_cmp_neq_f32_e32 vcc, -1.0, v0
	s_nop 1
	v_cndmask_b32_e32 v10, v192, v10, vcc
	v_cmp_lt_f32_e64 vcc, |v0|, s82
	s_nop 1
	v_cndmask_b32_e32 v0, v10, v0, vcc
.Lab_198:
	s_or_b64 exec, exec, s[70:71]
	v_mul_f32_e32 v10, 0xbfb8aa3b, v140
	v_exp_f32_e32 v10, v10
	v_mul_f32_e32 v0, v0, v162
	v_mul_f32_e32 v0, 0xbfb8aa3b, v0
	v_exp_f32_e32 v0, v0
	v_add_f32_e32 v10, 1.0, v10
	v_rcp_f32_e32 v10, v10
	ds_write2_b32 v220, v0, v10 offset0:32 offset1:64
	s_mov_b32 exec_lo, -1
	s_mov_b32 s82, s83
.Lab_skip:
.Ldc_b3:
	s_waitcnt lgkmcnt(0)
	s_barrier
	s_cmp_lt_u32 s60, 2
	s_cbranch_scc1 .Ldc_s4w
	s_and_b32 s61, s60, 1
	s_lshl_b32 s61, s61, 6
	v_mul_u32_u24_e32 v244, 0x480, v223
	v_lshl_add_u32 v244, v222, 2, v244
	v_add_u32_e32 v244, s61, v244
	v_add_u32_e32 v244, 0xe200, v244
	ds_read2_b32 v[34:35], v244 offset0:0 offset1:36
	ds_read2_b32 v[36:37], v244 offset0:72 offset1:108
	ds_read2_b32 v[38:39], v244 offset0:144 offset1:180
	ds_read2_b32 v[40:41], v244 offset0:216 offset1:252
	v_mul_u32_u24_e32 v245, 0x90, v222
	v_lshl_add_u32 v245, v223, 5, v245
	ds_read_b128 v[26:29], v245 offset:48640
	ds_read_b128 v[30:33], v245 offset:48656
	s_waitcnt lgkmcnt(0)
	v_mfma_f32_16x16x4_f32 v[58:61], v26, v34, v[58:61]
	v_mfma_f32_16x16x4_f32 v[58:61], v27, v35, v[58:61]
	v_mfma_f32_16x16x4_f32 v[58:61], v28, v36, v[58:61]
	v_mfma_f32_16x16x4_f32 v[58:61], v29, v37, v[58:61]
	v_mfma_f32_16x16x4_f32 v[58:61], v30, v38, v[58:61]
	v_mfma_f32_16x16x4_f32 v[58:61], v31, v39, v[58:61]
	v_mfma_f32_16x16x4_f32 v[58:61], v32, v40, v[58:61]
	v_mfma_f32_16x16x4_f32 v[58:61], v33, v41, v[58:61]
	ds_read_b128 v[26:29], v245 offset:50944
	ds_read_b128 v[30:33], v245 offset:50960
	s_waitcnt lgkmcnt(0)
	v_mfma_f32_16x16x4_f32 v[62:65], v26, v34, v[62:65]
	v_mfma_f32_16x16x4_f32 v[62:65], v27, v35, v[62:65]
	v_mfma_f32_16x16x4_f32 v[62:65], v28, v36, v[62:65]
	v_mfma_f32_16x16x4_f32 v[62:65], v29, v37, v[62:65]
	v_mfma_f32_16x16x4_f32 v[62:65], v30, v38, v[62:65]
	v_mfma_f32_16x16x4_f32 v[62:65], v31, v39, v[62:65]
	v_mfma_f32_16x16x4_f32 v[62:65], v32, v40, v[62:65]
	v_mfma_f32_16x16x4_f32 v[62:65], v33, v41, v[62:65]
	s_nop 7
	s_nop 3
	s_and_b32 s61, s60, 1
	s_lshl_b32 s61, s61, 6
	v_lshl_add_u32 v246, v223, 10, v248
	v_lshl_add_u32 v246, v222, 2, v246
	v_add_u32_e32 v246, s61, v246
	ds_write_b32 v246, v58 offset:17408
	ds_write_b32 v246, v59 offset:17664
	ds_write_b32 v246, v60 offset:17920
	ds_write_b32 v246, v61 offset:18176
	ds_write_b32 v246, v62 offset:21504
	ds_write_b32 v246, v63 offset:21760
	ds_write_b32 v246, v64 offset:22016
	ds_write_b32 v246, v65 offset:22272
	v_lshlrev_b32_e32 v245, 5, v223
	v_add_u32_e32 v245, 0x13780, v245
	ds_read_b128 v[42:45], v245
	ds_read_b128 v[46:49], v245 offset:16
	v_mov_b32_e32 v79, 0x1377c
	ds_read_b32 v78, v79
	v_mul_u32_u24_e32 v246, 0x880, v223
	v_lshl_add_u32 v246, v222, 2, v246
	s_and_b32 s61, s60, 1
	s_lshl_b32 s61, s61, 6
	s_add_i32 s61, s61, 0x11600
	v_mul_u32_u24_e32 v244, 0x210, v223
	v_lshl_add_u32 v244, v222, 2, v244
	v_add_u32_e32 v244, s61, v244
	ds_read_b32 v50, v246 offset:8896
	ds_read_b32 v51, v246 offset:9168
	ds_read_b32 v52, v246 offset:9440
	ds_read_b32 v53, v246 offset:9712
	ds_read_b32 v54, v246 offset:9984
	ds_read_b32 v55, v246 offset:10256
	ds_read_b32 v56, v246 offset:10528
	ds_read_b32 v57, v246 offset:10800
	ds_read_b32 v66, v244 offset:6336
	ds_read_b32 v67, v244 offset:6468
	ds_read_b32 v68, v244 offset:6600
	ds_read_b32 v69, v244 offset:6732
	s_waitcnt lgkmcnt(0)
	v_mul_f32_e32 v50, v42, v50
	v_mul_f32_e32 v51, v43, v51
	v_mul_f32_e32 v52, v44, v52
	v_mul_f32_e32 v53, v45, v53
	v_mul_f32_e32 v54, v46, v54
	v_mul_f32_e32 v55, v47, v55
	v_mul_f32_e32 v56, v48, v56
	v_mul_f32_e32 v57, v49, v57
	v_mul_f32_e32 v66, v78, v66
	v_mul_f32_e32 v67, v78, v67
	v_mul_f32_e32 v68, v78, v68
	v_mul_f32_e32 v69, v78, v69
	s_nop 1
	v_mfma_f32_16x16x4_f32 v[66:69], v50, v34, v[66:69]
	v_mfma_f32_16x16x4_f32 v[66:69], v51, v35, v[66:69]
	v_mfma_f32_16x16x4_f32 v[66:69], v52, v36, v[66:69]
	v_mfma_f32_16x16x4_f32 v[66:69], v53, v37, v[66:69]
	v_mfma_f32_16x16x4_f32 v[66:69], v54, v38, v[66:69]
	v_mfma_f32_16x16x4_f32 v[66:69], v55, v39, v[66:69]
	v_mfma_f32_16x16x4_f32 v[66:69], v56, v40, v[66:69]
	v_mfma_f32_16x16x4_f32 v[66:69], v57, v41, v[66:69]
	s_nop 7
	s_nop 3
	ds_write_b32 v244, v66 offset:6336
	ds_write_b32 v244, v67 offset:6468
	ds_write_b32 v244, v68 offset:6600
	ds_write_b32 v244, v69 offset:6732
	s_branch .Ldc_done
